# PLE output E stores nt
# speedup vs baseline: 1.0056x; 1.0010x over previous
; __device__ __forceinline__ unsigned cvt_pk_bf16(float lo, float hi) { unsigned r; asm volatile("v_cvt_pk_bf16_f32 %0, %1, %2" : "=v"(r) : "v"(lo), "v"(hi)); return r; }
;     __device__ __forceinline__ void operator()(const f32x4 (&acc)[2][2][4][2], const Unit& u_, int wr, int wc, int fr, int fq) const {
;     ...
;             for (int m = 0; m < 4; ++m) { const int row = row0 + ai * HALF + m * 16; bf16_t* rowp = E + (size_t)(rowb + ai * HALF + m * 16) * 1024 + colb; float s = 0.f;
; #pragma unroll
;                 for (int bj = 0; bj < 2; ++bj) { const f32x4 v0 = acc[ai][bj][m][0], v1 = acc[ai][bj][m][1];
;                     s += (v0[0] * v0[0] + v0[1] * v0[1]) + (v0[2] * v0[2] + v0[3] * v0[3]) + (v1[0] * v1[0] + v1[1] * v1[1]) + (v1[2] * v1[2] + v1[3] * v1[3]);
;                     u32x4 w; w.x = cvt_pk_bf16(v0[0], v0[1]); w.y = cvt_pk_bf16(v0[2], v0[3]); w.z = cvt_pk_bf16(v1[0], v1[1]); w.w = cvt_pk_bf16(v1[2], v1[3]);
;                     *(u32x4*)(rowp + bj * HALF) = xchg_bf16(xl, fr, fq, l, w); }
;                 s += __shfl_xor(s, 16); s += __shfl_xor(s, 32);
;                 if (fq == 0) atomicAdd(ssq + row, s);
;                 asm volatile("" ::: "memory"); }
.LBB0_855:
	v_mul_f32_e32 v151, v127, v127
	v_mul_f32_e32 v154, v129, v129
	v_fmac_f32_e32 v151, v126, v126
	v_fmac_f32_e32 v154, v128, v128
	v_add_f32_e32 v151, v151, v154
	v_mul_f32_e32 v154, v123, v123
	v_fmac_f32_e32 v154, v122, v122
	v_cvt_pk_bf16_f32 v126, v126, v127
	v_cvt_pk_bf16_f32 v127, v128, v129
	v_cvt_pk_bf16_f32 v128, v122, v123
	v_mul_f32_e32 v123, v125, v125
	v_add_f32_e32 v122, v154, v151
	v_fmac_f32_e32 v123, v124, v124
	s_lshl_b32 s10, s77, 8
	v_cvt_pk_bf16_f32 v129, v124, v125
	v_add_f32_e32 v122, v123, v122
	v_mul_f32_e32 v123, v119, v119
	v_mul_f32_e32 v124, v121, v121
	s_add_i32 s10, s10, s42
	ds_write_b128 v149, v[126:129]
	v_fmac_f32_e32 v123, v118, v118
	v_fmac_f32_e32 v124, v120, v120
	v_or_b32_e32 v142, s10, v146
	ds_read_b128 v[126:129], v150
	v_add_f32_e32 v123, v123, v124
	v_mul_f32_e32 v124, v115, v115
	v_ashrrev_i32_e32 v143, 31, v142
	v_fmac_f32_e32 v124, v114, v114
	v_lshl_or_b32 v140, s9, 8, v147
	v_lshlrev_b64 v[152:153], 11, v[142:143]
	v_add_f32_e32 v123, v124, v123
	v_mul_f32_e32 v124, v117, v117
	v_ashrrev_i32_e32 v141, 31, v140
	v_lshl_add_u64 v[152:153], s[18:19], 0, v[152:153]
	v_fmac_f32_e32 v124, v116, v116
	v_lshl_add_u64 v[152:153], v[140:141], 1, v[152:153]
	v_add_f32_e32 v123, v124, v123
	s_waitcnt lgkmcnt(0)
	global_store_dwordx4 v[152:153], v[126:129], off nt
	s_nop 1
	v_add_f32_e32 v126, v123, v122
	v_cvt_pk_bf16_f32 v122, v118, v119
	v_and_b32_e32 v119, 64, v229
	v_xor_b32_e32 v118, 16, v229
	v_add_u32_e32 v119, 64, v119
	v_cmp_lt_i32_e32 vcc, v118, v119
	v_cvt_pk_bf16_f32 v123, v120, v121
	v_cvt_pk_bf16_f32 v124, v114, v115
	v_xor_b32_e32 v114, 32, v229
	v_cvt_pk_bf16_f32 v125, v116, v117
	ds_write_b128 v149, v[122:125]
	v_cndmask_b32_e32 v118, v229, v118, vcc
	v_lshlrev_b32_e32 v118, 2, v118
	ds_bpermute_b32 v127, v118, v126
	v_cmp_lt_i32_e32 vcc, v114, v119
	ds_read_b128 v[120:123], v150
	s_waitcnt lgkmcnt(0)
	v_add_f32_e32 v117, v126, v127
	v_cndmask_b32_e32 v114, v229, v114, vcc
	v_lshlrev_b32_e32 v116, 2, v114
	ds_bpermute_b32 v119, v116, v117
	v_or_b32_e32 v114, s10, v144
	v_ashrrev_i32_e32 v115, 31, v114
	global_store_dwordx4 v[152:153], v[120:123], off offset:256 nt
	s_and_saveexec_b64 s[56:57], s[6:7]
	s_cbranch_execz .LBB0_857
	v_lshl_add_u64 v[120:121], v[114:115], 2, s[20:21]
	s_waitcnt lgkmcnt(0)
	v_add_f32_e32 v117, v117, v119
	global_atomic_add_f32 v[120:121], v117, off
.LBB0_857:
	s_or_b64 exec, exec, s[56:57]
	v_mul_f32_e32 v117, v111, v111
	s_waitcnt lgkmcnt(0)
	v_mul_f32_e32 v119, v113, v113
	v_fmac_f32_e32 v117, v110, v110
	v_fmac_f32_e32 v119, v112, v112
	v_add_f32_e32 v117, v117, v119
	v_mul_f32_e32 v119, v107, v107
	v_fmac_f32_e32 v119, v106, v106
	v_cvt_pk_bf16_f32 v110, v110, v111
	v_cvt_pk_bf16_f32 v111, v112, v113
	v_cvt_pk_bf16_f32 v112, v106, v107
	v_mul_f32_e32 v107, v109, v109
	v_add_f32_e32 v106, v119, v117
	v_fmac_f32_e32 v107, v108, v108
	v_cvt_pk_bf16_f32 v113, v108, v109
	v_add_f32_e32 v106, v107, v106
	v_mul_f32_e32 v107, v103, v103
	v_mul_f32_e32 v108, v105, v105
	v_fmac_f32_e32 v107, v102, v102
	v_fmac_f32_e32 v108, v104, v104
	v_add_f32_e32 v107, v107, v108
	v_mul_f32_e32 v108, v99, v99
	v_fmac_f32_e32 v108, v98, v98
	v_add_f32_e32 v107, v108, v107
	v_mul_f32_e32 v108, v101, v101
	v_fmac_f32_e32 v108, v100, v100
	v_add_f32_e32 v107, v108, v107
	ds_write_b128 v149, v[110:113]
	v_add_f32_e32 v106, v107, v106
	v_or_b32_e32 v120, 16, v142
	ds_read_b128 v[110:113], v150
	ds_bpermute_b32 v107, v118, v106
	v_ashrrev_i32_e32 v121, 31, v120
	v_lshlrev_b64 v[120:121], 11, v[120:121]
	v_lshl_add_u64 v[120:121], s[18:19], 0, v[120:121]
	v_lshl_add_u64 v[120:121], v[140:141], 1, v[120:121]
	s_waitcnt lgkmcnt(0)
	global_store_dwordx4 v[120:121], v[110:113], off nt
	v_cvt_pk_bf16_f32 v102, v102, v103
	v_cvt_pk_bf16_f32 v103, v104, v105
	v_cvt_pk_bf16_f32 v104, v98, v99
	v_cvt_pk_bf16_f32 v105, v100, v101
	ds_write_b128 v149, v[102:105]
	v_add_f32_e32 v98, v106, v107
	ds_read_b128 v[100:103], v150
	ds_bpermute_b32 v99, v116, v98
	s_waitcnt lgkmcnt(0)
	global_store_dwordx4 v[120:121], v[100:103], off offset:256 nt
	s_and_saveexec_b64 s[56:57], s[6:7]
	s_cbranch_execz .LBB0_859
	v_lshl_add_u64 v[100:101], v[114:115], 2, s[20:21]
	v_add_f32_e32 v98, v98, v99
	global_atomic_add_f32 v[100:101], v98, off offset:64
.LBB0_859:
	s_or_b64 exec, exec, s[56:57]
	v_mul_f32_e32 v100, v95, v95
	v_mul_f32_e32 v101, v97, v97
	v_fmac_f32_e32 v100, v94, v94
	v_fmac_f32_e32 v101, v96, v96
	v_add_f32_e32 v100, v100, v101
	v_mul_f32_e32 v101, v91, v91
	v_fmac_f32_e32 v101, v90, v90
	v_cvt_pk_bf16_f32 v94, v94, v95
	v_cvt_pk_bf16_f32 v95, v96, v97
	v_cvt_pk_bf16_f32 v96, v90, v91
	v_mul_f32_e32 v91, v93, v93
	v_add_f32_e32 v90, v101, v100
	v_fmac_f32_e32 v91, v92, v92
	v_cvt_pk_bf16_f32 v97, v92, v93
	v_add_f32_e32 v90, v91, v90
	v_mul_f32_e32 v91, v87, v87
	v_mul_f32_e32 v92, v89, v89
	v_fmac_f32_e32 v91, v86, v86
	v_fmac_f32_e32 v92, v88, v88
	v_add_f32_e32 v91, v91, v92
	v_mul_f32_e32 v92, v83, v83
	v_fmac_f32_e32 v92, v82, v82
	v_add_f32_e32 v91, v92, v91
	v_mul_f32_e32 v92, v85, v85
	v_fmac_f32_e32 v92, v84, v84
	v_add_f32_e32 v91, v92, v91
	ds_write_b128 v149, v[94:97]
	v_add_f32_e32 v90, v91, v90
	v_or_b32_e32 v98, 32, v142
	ds_read_b128 v[94:97], v150
	ds_bpermute_b32 v91, v118, v90
	v_ashrrev_i32_e32 v99, 31, v98
	v_lshlrev_b64 v[98:99], 11, v[98:99]
	v_lshl_add_u64 v[98:99], s[18:19], 0, v[98:99]
	v_lshl_add_u64 v[98:99], v[140:141], 1, v[98:99]
	s_waitcnt lgkmcnt(0)
	global_store_dwordx4 v[98:99], v[94:97], off nt
	v_cvt_pk_bf16_f32 v86, v86, v87
	v_cvt_pk_bf16_f32 v87, v88, v89
	v_cvt_pk_bf16_f32 v88, v82, v83
	v_cvt_pk_bf16_f32 v89, v84, v85
	ds_write_b128 v149, v[86:89]
	v_add_f32_e32 v82, v90, v91
	ds_read_b128 v[84:87], v150
	ds_bpermute_b32 v83, v116, v82
	s_waitcnt lgkmcnt(0)
	global_store_dwordx4 v[98:99], v[84:87], off offset:256 nt
	s_and_saveexec_b64 s[56:57], s[6:7]
	s_cbranch_execz .LBB0_861
	v_lshl_add_u64 v[84:85], v[114:115], 2, s[20:21]
	v_add_f32_e32 v82, v82, v83
	global_atomic_add_f32 v[84:85], v82, off offset:128
; __device__ __forceinline__ unsigned cvt_pk_bf16(float lo, float hi) { unsigned r; asm volatile("v_cvt_pk_bf16_f32 %0, %1, %2" : "=v"(r) : "v"(lo), "v"(hi)); return r; }
;     __device__ __forceinline__ void operator()(const f32x4 (&acc)[2][2][4][2], const Unit& u_, int wr, int wc, int fr, int fq) const {
;     ...
;             for (int m = 0; m < 4; ++m) { const int row = row0 + ai * HALF + m * 16; bf16_t* rowp = E + (size_t)(rowb + ai * HALF + m * 16) * 1024 + colb; float s = 0.f;
; #pragma unroll
;                 for (int bj = 0; bj < 2; ++bj) { const f32x4 v0 = acc[ai][bj][m][0], v1 = acc[ai][bj][m][1];
;                     s += (v0[0] * v0[0] + v0[1] * v0[1]) + (v0[2] * v0[2] + v0[3] * v0[3]) + (v1[0] * v1[0] + v1[1] * v1[1]) + (v1[2] * v1[2] + v1[3] * v1[3]);
;                     u32x4 w; w.x = cvt_pk_bf16(v0[0], v0[1]); w.y = cvt_pk_bf16(v0[2], v0[3]); w.z = cvt_pk_bf16(v1[0], v1[1]); w.w = cvt_pk_bf16(v1[2], v1[3]);
;                     *(u32x4*)(rowp + bj * HALF) = xchg_bf16(xl, fr, fq, l, w); }
;                 s += __shfl_xor(s, 16); s += __shfl_xor(s, 32);
;                 if (fq == 0) atomicAdd(ssq + row, s);
;                 asm volatile("" ::: "memory"); }
.LBB0_861:
	s_or_b64 exec, exec, s[56:57]
	v_mul_f32_e32 v84, v79, v79
	v_mul_f32_e32 v85, v81, v81
	v_fmac_f32_e32 v84, v78, v78
	v_fmac_f32_e32 v85, v80, v80
	v_add_f32_e32 v84, v84, v85
	v_mul_f32_e32 v85, v75, v75
	v_fmac_f32_e32 v85, v74, v74
	v_cvt_pk_bf16_f32 v78, v78, v79
	v_cvt_pk_bf16_f32 v79, v80, v81
	v_cvt_pk_bf16_f32 v80, v74, v75
	v_mul_f32_e32 v75, v77, v77
	v_add_f32_e32 v74, v85, v84
	v_fmac_f32_e32 v75, v76, v76
	v_cvt_pk_bf16_f32 v81, v76, v77
	v_add_f32_e32 v74, v75, v74
	v_mul_f32_e32 v75, v71, v71
	v_mul_f32_e32 v76, v73, v73
	v_fmac_f32_e32 v75, v70, v70
	v_fmac_f32_e32 v76, v72, v72
	v_add_f32_e32 v75, v75, v76
	v_mul_f32_e32 v76, v67, v67
	v_fmac_f32_e32 v76, v66, v66
	v_add_f32_e32 v75, v76, v75
	v_mul_f32_e32 v76, v69, v69
	v_fmac_f32_e32 v76, v68, v68
	v_add_f32_e32 v75, v76, v75
	ds_write_b128 v149, v[78:81]
	v_add_f32_e32 v74, v75, v74
	v_or_b32_e32 v82, 48, v142
	ds_read_b128 v[78:81], v150
	ds_bpermute_b32 v75, v118, v74
	v_ashrrev_i32_e32 v83, 31, v82
	v_lshlrev_b64 v[82:83], 11, v[82:83]
	v_lshl_add_u64 v[82:83], s[18:19], 0, v[82:83]
	v_lshl_add_u64 v[82:83], v[140:141], 1, v[82:83]
	s_waitcnt lgkmcnt(0)
	global_store_dwordx4 v[82:83], v[78:81], off nt
	v_cvt_pk_bf16_f32 v70, v70, v71
	v_cvt_pk_bf16_f32 v71, v72, v73
	v_cvt_pk_bf16_f32 v72, v66, v67
	v_cvt_pk_bf16_f32 v73, v68, v69
	ds_write_b128 v149, v[70:73]
	v_add_f32_e32 v66, v74, v75
	ds_read_b128 v[68:71], v150
	ds_bpermute_b32 v67, v116, v66
	s_waitcnt lgkmcnt(0)
	global_store_dwordx4 v[82:83], v[68:71], off offset:256 nt
	s_and_saveexec_b64 s[56:57], s[6:7]
	s_cbranch_execz .LBB0_863
	v_lshl_add_u64 v[68:69], v[114:115], 2, s[20:21]
	v_add_f32_e32 v66, v66, v67
	global_atomic_add_f32 v[68:69], v66, off offset:192
.LBB0_863:
	s_or_b64 exec, exec, s[56:57]
	v_mul_f32_e32 v68, v63, v63
	v_mul_f32_e32 v69, v65, v65
	v_fmac_f32_e32 v68, v62, v62
	v_fmac_f32_e32 v69, v64, v64
	v_add_f32_e32 v68, v68, v69
	v_mul_f32_e32 v69, v59, v59
	v_fmac_f32_e32 v69, v58, v58
	v_add_f32_e32 v68, v69, v68
	v_mul_f32_e32 v69, v61, v61
	v_cvt_pk_bf16_f32 v62, v62, v63
	v_cvt_pk_bf16_f32 v63, v64, v65
	v_cvt_pk_bf16_f32 v64, v58, v59
	v_cvt_pk_bf16_f32 v65, v60, v61
	ds_write_b128 v149, v[62:65]
	v_lshlrev_b64 v[66:67], 11, v[142:143]
	v_fmac_f32_e32 v69, v60, v60
	ds_read_b128 v[58:61], v150
	v_lshl_add_u64 v[66:67], s[18:19], 0, v[66:67]
	v_lshl_add_u64 v[66:67], v[140:141], 1, v[66:67]
	s_mov_b32 s9, 0x40000
	v_add_co_u32_e32 v62, vcc, s9, v66
	v_add_f32_e32 v68, v69, v68
	s_nop 0
	v_addc_co_u32_e32 v63, vcc, 0, v67, vcc
	s_waitcnt lgkmcnt(0)
	global_store_dwordx4 v[62:63], v[58:61], off nt
	s_mov_b64 s[34:35], 0x40000
	s_nop 0
	v_mul_f32_e32 v58, v55, v55
	v_mul_f32_e32 v59, v57, v57
	v_fmac_f32_e32 v58, v54, v54
	v_fmac_f32_e32 v59, v56, v56
	v_add_f32_e32 v58, v58, v59
	v_mul_f32_e32 v59, v51, v51
	v_fmac_f32_e32 v59, v50, v50
	v_add_f32_e32 v58, v59, v58
	v_mul_f32_e32 v59, v53, v53
	v_fmac_f32_e32 v59, v52, v52
	v_add_f32_e32 v58, v59, v58
	v_add_f32_e32 v58, v58, v68
	ds_bpermute_b32 v59, v118, v58
	v_cvt_pk_bf16_f32 v54, v54, v55
	v_cvt_pk_bf16_f32 v55, v56, v57
	v_cvt_pk_bf16_f32 v56, v50, v51
	v_cvt_pk_bf16_f32 v57, v52, v53
	ds_write_b128 v149, v[54:57]
	s_waitcnt lgkmcnt(0)
	v_add_f32_e32 v50, v58, v59
	ds_read_b128 v[52:55], v150
	ds_bpermute_b32 v51, v116, v50
	v_lshl_add_u64 v[56:57], v[66:67], 0, s[34:35]
	s_waitcnt lgkmcnt(0)
	global_store_dwordx4 v[56:57], v[52:55], off offset:256 nt
	s_and_saveexec_b64 s[56:57], s[6:7]
	s_cbranch_execz .LBB0_865
	v_lshl_add_u64 v[52:53], v[114:115], 2, s[20:21]
	v_add_f32_e32 v50, v50, v51
	global_atomic_add_f32 v[52:53], v50, off offset:512
; __device__ __forceinline__ unsigned cvt_pk_bf16(float lo, float hi) { unsigned r; asm volatile("v_cvt_pk_bf16_f32 %0, %1, %2" : "=v"(r) : "v"(lo), "v"(hi)); return r; }
;     __device__ __forceinline__ void operator()(const f32x4 (&acc)[2][2][4][2], const Unit& u_, int wr, int wc, int fr, int fq) const {
;     ...
;             for (int m = 0; m < 4; ++m) { const int row = row0 + ai * HALF + m * 16; bf16_t* rowp = E + (size_t)(rowb + ai * HALF + m * 16) * 1024 + colb; float s = 0.f;
; #pragma unroll
;                 for (int bj = 0; bj < 2; ++bj) { const f32x4 v0 = acc[ai][bj][m][0], v1 = acc[ai][bj][m][1];
;                     s += (v0[0] * v0[0] + v0[1] * v0[1]) + (v0[2] * v0[2] + v0[3] * v0[3]) + (v1[0] * v1[0] + v1[1] * v1[1]) + (v1[2] * v1[2] + v1[3] * v1[3]);
;                     u32x4 w; w.x = cvt_pk_bf16(v0[0], v0[1]); w.y = cvt_pk_bf16(v0[2], v0[3]); w.z = cvt_pk_bf16(v1[0], v1[1]); w.w = cvt_pk_bf16(v1[2], v1[3]);
;                     *(u32x4*)(rowp + bj * HALF) = xchg_bf16(xl, fr, fq, l, w); }
;                 s += __shfl_xor(s, 16); s += __shfl_xor(s, 32);
;                 if (fq == 0) atomicAdd(ssq + row, s);
;                 asm volatile("" ::: "memory"); }
.LBB0_865:
	s_or_b64 exec, exec, s[56:57]
	v_mul_f32_e32 v50, v47, v47
	v_mul_f32_e32 v51, v49, v49
	v_fmac_f32_e32 v50, v46, v46
	v_fmac_f32_e32 v51, v48, v48
	v_add_f32_e32 v50, v50, v51
	v_mul_f32_e32 v51, v43, v43
	v_fmac_f32_e32 v51, v42, v42
	v_add_f32_e32 v50, v51, v50
	v_mul_f32_e32 v51, v45, v45
	v_cvt_pk_bf16_f32 v46, v46, v47
	v_cvt_pk_bf16_f32 v47, v48, v49
	v_cvt_pk_bf16_f32 v48, v42, v43
	v_cvt_pk_bf16_f32 v49, v44, v45
	ds_write_b128 v149, v[46:49]
	v_fmac_f32_e32 v51, v44, v44
	ds_read_b128 v[42:45], v150
	s_mov_b32 s9, 0x48000
	v_add_co_u32_e32 v46, vcc, s9, v66
	v_add_f32_e32 v50, v51, v50
	s_nop 0
	v_addc_co_u32_e32 v47, vcc, 0, v67, vcc
	s_waitcnt lgkmcnt(0)
	global_store_dwordx4 v[46:47], v[42:45], off nt
	s_mov_b64 s[34:35], 0x48000
	s_nop 0
	v_mul_f32_e32 v42, v39, v39
	v_mul_f32_e32 v43, v41, v41
	v_fmac_f32_e32 v42, v38, v38
	v_fmac_f32_e32 v43, v40, v40
	v_add_f32_e32 v42, v42, v43
	v_mul_f32_e32 v43, v35, v35
	v_fmac_f32_e32 v43, v34, v34
	v_add_f32_e32 v42, v43, v42
	v_mul_f32_e32 v43, v37, v37
	v_fmac_f32_e32 v43, v36, v36
	v_add_f32_e32 v42, v43, v42
	v_add_f32_e32 v42, v42, v50
	ds_bpermute_b32 v43, v118, v42
	v_cvt_pk_bf16_f32 v38, v38, v39
	v_cvt_pk_bf16_f32 v39, v40, v41
	v_cvt_pk_bf16_f32 v40, v34, v35
	v_cvt_pk_bf16_f32 v41, v36, v37
	ds_write_b128 v149, v[38:41]
	s_waitcnt lgkmcnt(0)
	v_add_f32_e32 v34, v42, v43
	ds_read_b128 v[36:39], v150
	ds_bpermute_b32 v35, v116, v34
	v_lshl_add_u64 v[40:41], v[66:67], 0, s[34:35]
	s_waitcnt lgkmcnt(0)
	global_store_dwordx4 v[40:41], v[36:39], off offset:256 nt
	s_and_saveexec_b64 s[56:57], s[6:7]
	s_cbranch_execz .LBB0_867
	v_lshl_add_u64 v[36:37], v[114:115], 2, s[20:21]
	v_add_f32_e32 v34, v34, v35
	global_atomic_add_f32 v[36:37], v34, off offset:576
.LBB0_867:
	s_or_b64 exec, exec, s[56:57]
	v_mul_f32_e32 v36, v31, v31
	v_mul_f32_e32 v37, v33, v33
	v_fmac_f32_e32 v36, v30, v30
	v_fmac_f32_e32 v37, v32, v32
	v_add_f32_e32 v36, v36, v37
	v_mul_f32_e32 v37, v27, v27
	v_fmac_f32_e32 v37, v26, v26
	v_add_f32_e32 v36, v37, v36
	v_mul_f32_e32 v37, v29, v29
	v_cvt_pk_bf16_f32 v30, v30, v31
	v_cvt_pk_bf16_f32 v31, v32, v33
	v_cvt_pk_bf16_f32 v32, v26, v27
	v_cvt_pk_bf16_f32 v33, v28, v29
	ds_write_b128 v149, v[30:33]
	v_lshlrev_b64 v[34:35], 11, v[142:143]
	v_fmac_f32_e32 v37, v28, v28
	ds_read_b128 v[26:29], v150
	v_lshl_add_u64 v[34:35], s[18:19], 0, v[34:35]
	v_lshl_add_u64 v[34:35], v[140:141], 1, v[34:35]
	s_mov_b32 s9, 0x50000
	v_add_co_u32_e32 v30, vcc, s9, v34
	v_add_f32_e32 v36, v37, v36
	s_nop 0
	v_addc_co_u32_e32 v31, vcc, 0, v35, vcc
	s_waitcnt lgkmcnt(0)
	global_store_dwordx4 v[30:31], v[26:29], off nt
	s_mov_b64 s[34:35], 0x50000
	s_nop 0
	v_mul_f32_e32 v26, v23, v23
	v_mul_f32_e32 v27, v25, v25
	v_fmac_f32_e32 v26, v22, v22
	v_fmac_f32_e32 v27, v24, v24
	v_add_f32_e32 v26, v26, v27
	v_mul_f32_e32 v27, v19, v19
	v_fmac_f32_e32 v27, v18, v18
	v_add_f32_e32 v26, v27, v26
	v_mul_f32_e32 v27, v21, v21
	v_fmac_f32_e32 v27, v20, v20
	v_add_f32_e32 v26, v27, v26
	v_add_f32_e32 v26, v26, v36
	ds_bpermute_b32 v27, v118, v26
	v_cvt_pk_bf16_f32 v22, v22, v23
	v_cvt_pk_bf16_f32 v23, v24, v25
	v_cvt_pk_bf16_f32 v24, v18, v19
	v_cvt_pk_bf16_f32 v25, v20, v21
	ds_write_b128 v149, v[22:25]
	s_waitcnt lgkmcnt(0)
	v_add_f32_e32 v18, v26, v27
	ds_read_b128 v[20:23], v150
	ds_bpermute_b32 v19, v116, v18
	v_lshl_add_u64 v[24:25], v[34:35], 0, s[34:35]
	s_waitcnt lgkmcnt(0)
	global_store_dwordx4 v[24:25], v[20:23], off offset:256 nt
	s_and_saveexec_b64 s[56:57], s[6:7]
	s_cbranch_execz .LBB0_869
	v_lshl_add_u64 v[20:21], v[114:115], 2, s[20:21]
	v_add_f32_e32 v18, v18, v19
	global_atomic_add_f32 v[20:21], v18, off offset:640
.LBB0_869:
	s_or_b64 exec, exec, s[56:57]
	v_mul_f32_e32 v18, v15, v15
	v_mul_f32_e32 v19, v17, v17
	v_fmac_f32_e32 v18, v14, v14
	v_fmac_f32_e32 v19, v16, v16
	v_add_f32_e32 v18, v18, v19
	v_mul_f32_e32 v19, v11, v11
	v_fmac_f32_e32 v19, v10, v10
	v_add_f32_e32 v18, v19, v18
	v_mul_f32_e32 v19, v13, v13
	v_cvt_pk_bf16_f32 v14, v14, v15
	v_cvt_pk_bf16_f32 v15, v16, v17
	v_cvt_pk_bf16_f32 v16, v10, v11
	v_cvt_pk_bf16_f32 v17, v12, v13
	ds_write_b128 v149, v[14:17]
	v_fmac_f32_e32 v19, v12, v12
	ds_read_b128 v[10:13], v150
	s_mov_b32 s9, 0x58000
	v_add_co_u32_e32 v14, vcc, s9, v34
	v_add_f32_e32 v18, v19, v18
	s_nop 0
	v_addc_co_u32_e32 v15, vcc, 0, v35, vcc
	s_waitcnt lgkmcnt(0)
	global_store_dwordx4 v[14:15], v[10:13], off nt
	s_mov_b64 s[34:35], 0x58000
	s_nop 0
	v_mul_f32_e32 v10, v7, v7
	v_mul_f32_e32 v11, v9, v9
	v_fmac_f32_e32 v10, v6, v6
	v_fmac_f32_e32 v11, v8, v8
	v_add_f32_e32 v10, v10, v11
	v_mul_f32_e32 v11, v3, v3
	v_fmac_f32_e32 v11, v2, v2
	v_add_f32_e32 v10, v11, v10
	v_mul_f32_e32 v11, v5, v5
	v_fmac_f32_e32 v11, v4, v4
	v_add_f32_e32 v10, v11, v10
	v_add_f32_e32 v10, v10, v18
	ds_bpermute_b32 v11, v118, v10
	v_cvt_pk_bf16_f32 v6, v6, v7
	v_cvt_pk_bf16_f32 v7, v8, v9
	v_cvt_pk_bf16_f32 v8, v2, v3
	v_cvt_pk_bf16_f32 v9, v4, v5
	ds_write_b128 v149, v[6:9]
	s_waitcnt lgkmcnt(0)
	v_add_f32_e32 v2, v10, v11
	ds_read_b128 v[4:7], v150
	ds_bpermute_b32 v3, v116, v2
	v_lshl_add_u64 v[8:9], v[34:35], 0, s[34:35]
	s_waitcnt lgkmcnt(0)
	global_store_dwordx4 v[8:9], v[4:7], off offset:256 nt
	s_and_saveexec_b64 s[56:57], s[6:7]
	s_cbranch_execz .LBB0_871
	v_lshl_add_u64 v[4:5], v[114:115], 2, s[20:21]
	v_add_f32_e32 v2, v2, v3
	global_atomic_add_f32 v[4:5], v2, off offset:704
